# ssd_pass2: the two workgroup barriers in front of the conv weight loads moved below those loads
# speedup vs baseline: 1.0071x; 1.0071x over previous
; #define LAS __attribute__((address_space(3)))
; DI float silu_f(float x) { return x * __builtin_amdgcn_rcpf(1.0f + __expf(-x)); }
; DI u32x4 pack8(const float (&v)[8]) { u32x4 w; w.x = pk2(v[0], v[1]); w.y = pk2(v[2], v[3]); w.z = pk2(v[4], v[5]); w.w = pk2(v[6], v[7]); return w; }
; template <bool SILU>
; DI void conv_compute(const u32x4 (&raw)[7], const float* w, int C, const float* bias, float (&out)[4][8]) {
;     float wv[4][8], bv[8], x[7][8];
; #pragma unroll
;     for (int j = 0; j < 4; ++j) { const f32x4 a = *(const f32x4*)(w + (size_t)j * C), b = *(const f32x4*)(w + (size_t)j * C + 4);
;         wv[j][0] = a[0]; wv[j][1] = a[1]; wv[j][2] = a[2]; wv[j][3] = a[3]; wv[j][4] = b[0]; wv[j][5] = b[1]; wv[j][6] = b[2]; wv[j][7] = b[3]; }
;     { const f32x4 a = *(const f32x4*)bias, b = *(const f32x4*)(bias + 4); bv[0] = a[0]; bv[1] = a[1]; bv[2] = a[2]; bv[3] = a[3]; bv[4] = b[0]; bv[5] = b[1]; bv[6] = b[2]; bv[7] = b[3]; }
; #pragma unroll
;     for (int i = 0; i < 7; ++i) unpack8(raw[i], x[i]);
; #pragma unroll
;     for (int t = 0; t < 4; ++t)
; #pragma unroll
;         for (int c = 0; c < 8; ++c) { float v = bv[c] + wv[0][c] * x[t][c] + wv[1][c] * x[t + 1][c] + wv[2][c] * x[t + 2][c] + wv[3][c] * x[t + 3][c]; out[t][c] = SILU ? silu_f(v) : v; }
; DI void ssd_pass2(LAS unsigned char* lds, const Args& a, const LayerP& P, int unit, int wv) {
;     ...
;         wgemm<4, 2>(acc, R1 + hh * 64 * PT, PT, Cm + lr * PT, PT, 128, lane);
; #pragma unroll
;         for (int ni = 0; ni < 2; ++ni) { const float e = __expf(acs[hh * 128 + lr + ni * 16 + r]);
; #pragma unroll
;             for (int mi = 0; mi < 4; ++mi) acc[mi][ni] = acc[mi][ni] * e; }
;         __syncthreads();
;         { float o[4][8]; conv_compute<true>(rawB, P.ssd_cw + 256 + g * 128 + cv * 8, 768, P.ssd_cb + 256 + g * 128 + cv * 8, o);
; #pragma unroll
;           for (int t = 0; t < 4; ++t) *(LAS u32x4*)(R1 + (t0 + t) * PT + cv * 8) = pack8(o[t]); }
.LBB0_1402:
	ds_read_b128 v[64:67], v63
	ds_read_b128 v[68:71], v62
	ds_read_b128 v[72:75], v62 offset:4352
	s_add_i32 s2, s2, 32
	s_cmpk_lt_u32 s2, 0x60
	v_add_u32_e32 v62, 64, v62
	s_waitcnt lgkmcnt(1)
	v_mfma_f32_16x16x32_bf16 v[30:33], v[64:67], v[68:71], v[30:33]
	s_waitcnt lgkmcnt(0)
	v_mfma_f32_16x16x32_bf16 v[22:25], v[64:67], v[72:75], v[22:25]
	ds_read_b128 v[64:67], v63 offset:4352
	s_waitcnt lgkmcnt(0)
	v_mfma_f32_16x16x32_bf16 v[26:29], v[64:67], v[68:71], v[26:29]
	v_mfma_f32_16x16x32_bf16 v[14:17], v[64:67], v[72:75], v[14:17]
	ds_read_b128 v[64:67], v63 offset:8704
	s_waitcnt lgkmcnt(0)
	v_mfma_f32_16x16x32_bf16 v[18:21], v[64:67], v[68:71], v[18:21]
	v_mfma_f32_16x16x32_bf16 v[6:9], v[64:67], v[72:75], v[6:9]
	ds_read_b128 v[64:67], v63 offset:13056
	v_add_u32_e32 v63, 64, v63
	s_waitcnt lgkmcnt(0)
	v_mfma_f32_16x16x32_bf16 v[10:13], v[64:67], v[68:71], v[10:13]
	v_mfma_f32_16x16x32_bf16 v[2:5], v[64:67], v[72:75], v[2:5]
	s_cbranch_scc1 .LBB0_1402
	v_readlane_b32 s2, v254, 13
	v_add_co_u32_e32 v72, vcc, 0x1000, v102
	s_nop 0
	v_lshl_add_u32 v62, v120, 2, s2
	s_mov_b64 s[2:3], 0x400
	v_lshl_add_u64 v[70:71], v[102:103], 0, s[2:3]
	s_mov_b64 s[2:3], 0x1c00
	ds_read2_b32 v[110:111], v62 offset1:16
	s_waitcnt lgkmcnt(0)
	global_load_dwordx4 v[62:65], v[102:103], off offset:1040
	global_load_dwordx4 v[82:85], v[102:103], off offset:1024
	global_load_dwordx4 v[66:69], v[70:71], off offset:3088
	global_load_dwordx4 v[86:89], v[70:71], off offset:3072
	v_lshl_add_u64 v[70:71], v[102:103], 0, s[2:3]
	s_mov_b64 s[2:3], 0x2800
	v_addc_co_u32_e32 v73, vcc, 0, v103, vcc
	v_lshl_add_u64 v[74:75], v[102:103], 0, s[2:3]
	global_load_dwordx4 v[90:93], v[72:73], off offset:3072
	s_nop 0
	global_load_dwordx4 v[70:73], v[70:71], off offset:16
	s_nop 0
	global_load_dwordx4 v[94:97], v[104:105], off offset:2048
	s_nop 0
	global_load_dwordx4 v[74:77], v[74:75], off offset:16
	s_nop 0
	global_load_dwordx4 v[78:81], v[108:109], off offset:1040
	global_load_dwordx4 v[98:101], v[108:109], off offset:1024
	s_barrier
	s_waitcnt vmcnt(10)
	v_lshlrev_b32_e32 v144, 16, v34
	v_and_b32_e32 v145, 0xffff0000, v34
	v_lshlrev_b32_e32 v114, 16, v38
	v_and_b32_e32 v115, 0xffff0000, v38
	v_lshlrev_b32_e32 v112, 16, v42
	v_and_b32_e32 v113, 0xffff0000, v42
	v_lshlrev_b32_e32 v134, 16, v50
	v_and_b32_e32 v135, 0xffff0000, v50
	v_lshlrev_b32_e32 v136, 16, v46
	v_and_b32_e32 v137, 0xffff0000, v46
	v_lshlrev_b32_e32 v138, 16, v58
	v_and_b32_e32 v139, 0xffff0000, v58
	v_lshlrev_b32_e32 v140, 16, v54
	v_and_b32_e32 v141, 0xffff0000, v54
	v_lshlrev_b32_e32 v38, 16, v39
	v_and_b32_e32 v39, 0xffff0000, v39
	v_lshlrev_b32_e32 v42, 16, v43
	v_and_b32_e32 v43, 0xffff0000, v43
	v_lshlrev_b32_e32 v50, 16, v51
	v_and_b32_e32 v51, 0xffff0000, v51
	v_lshlrev_b32_e32 v46, 16, v47
	v_and_b32_e32 v47, 0xffff0000, v47
	v_lshlrev_b32_e32 v58, 16, v59
	v_and_b32_e32 v59, 0xffff0000, v59
	v_lshlrev_b32_e32 v54, 16, v55
	v_and_b32_e32 v55, 0xffff0000, v55
	s_waitcnt vmcnt(0)
	v_pk_fma_f32 v[144:145], v[82:83], v[144:145], v[98:99]
	v_pk_fma_f32 v[142:143], v[82:83], v[114:115], v[98:99]
	v_pk_fma_f32 v[114:115], v[86:87], v[114:115], v[144:145]
	v_pk_fma_f32 v[116:117], v[82:83], v[112:113], v[98:99]
	v_pk_fma_f32 v[142:143], v[86:87], v[112:113], v[142:143]
	v_pk_fma_f32 v[112:113], v[90:91], v[112:113], v[114:115]
	v_pk_fma_f32 v[116:117], v[86:87], v[134:135], v[116:117]
	v_pk_fma_f32 v[112:113], v[94:95], v[134:135], v[112:113]
	v_pk_fma_f32 v[116:117], v[90:91], v[136:137], v[116:117]
	v_mul_f32_e32 v34, 0xbfb8aa3b, v112
	v_exp_f32_e32 v34, v34
	v_pk_fma_f32 v[116:117], v[94:95], v[138:139], v[116:117]
	v_pk_fma_f32 v[82:83], v[82:83], v[134:135], v[98:99]
	v_add_f32_e32 v34, 1.0, v34
	v_rcp_f32_e32 v114, v34
	v_mul_f32_e32 v34, 0xbfb8aa3b, v113
	v_exp_f32_e32 v34, v34
	v_pk_fma_f32 v[82:83], v[86:87], v[136:137], v[82:83]
	v_add_f32_e32 v34, 1.0, v34
	v_rcp_f32_e32 v115, v34
	v_pk_fma_f32 v[82:83], v[90:91], v[138:139], v[82:83]
	v_pk_mul_f32 v[112:113], v[112:113], v[114:115]
	v_pk_fma_f32 v[114:115], v[90:91], v[134:135], v[142:143]
	v_pk_fma_f32 v[82:83], v[94:95], v[140:141], v[82:83]
	v_pk_fma_f32 v[114:115], v[94:95], v[136:137], v[114:115]
	v_pk_fma_f32 v[90:91], v[84:85], v[38:39], v[100:101]
	v_mul_f32_e32 v34, 0xbfb8aa3b, v114
	v_exp_f32_e32 v34, v34
	v_pk_fma_f32 v[90:91], v[88:89], v[42:43], v[90:91]
	v_lshlrev_b32_e32 v94, 16, v36
	v_and_b32_e32 v95, 0xffff0000, v36
	v_add_f32_e32 v34, 1.0, v34
	v_rcp_f32_e32 v142, v34
	v_mul_f32_e32 v34, 0xbfb8aa3b, v115
	v_exp_f32_e32 v34, v34
	v_pk_fma_f32 v[94:95], v[62:63], v[94:95], v[78:79]
	v_add_f32_e32 v34, 1.0, v34
	v_rcp_f32_e32 v143, v34
	v_mul_f32_e32 v34, 0xbfb8aa3b, v116
	v_exp_f32_e32 v34, v34
	v_pk_mul_f32 v[114:115], v[114:115], v[142:143]
	v_add_f32_e32 v34, 1.0, v34
	v_rcp_f32_e32 v142, v34
	v_mul_f32_e32 v34, 0xbfb8aa3b, v117
	v_exp_f32_e32 v34, v34
	s_nop 0
	v_add_f32_e32 v34, 1.0, v34
	v_rcp_f32_e32 v143, v34
	v_mul_f32_e32 v34, 0xbfb8aa3b, v82
	v_exp_f32_e32 v34, v34
	v_pk_mul_f32 v[116:117], v[116:117], v[142:143]
	v_add_f32_e32 v34, 1.0, v34
	v_rcp_f32_e32 v86, v34
	v_mul_f32_e32 v34, 0xbfb8aa3b, v83
	v_exp_f32_e32 v34, v34
	s_nop 0
	v_add_f32_e32 v34, 1.0, v34
	v_rcp_f32_e32 v87, v34
	v_lshlrev_b32_e32 v34, 16, v35
	v_and_b32_e32 v35, 0xffff0000, v35
	v_pk_fma_f32 v[34:35], v[84:85], v[34:35], v[100:101]
	v_pk_mul_f32 v[82:83], v[82:83], v[86:87]
	v_pk_fma_f32 v[34:35], v[88:89], v[38:39], v[34:35]
	v_pk_fma_f32 v[86:87], v[84:85], v[42:43], v[100:101]
	v_pk_fma_f32 v[34:35], v[92:93], v[42:43], v[34:35]
	s_nop 0
	v_pk_fma_f32 v[34:35], v[96:97], v[50:51], v[34:35]
	s_nop 0
	v_mul_f32_e32 v38, 0xbfb8aa3b, v34
; DI float silu_f(float x) { return x * __builtin_amdgcn_rcpf(1.0f + __expf(-x)); }
; template <bool SILU>
; DI void conv_compute(const u32x4 (&raw)[7], const float* w, int C, const float* bias, float (&out)[4][8]) {
;     float wv[4][8], bv[8], x[7][8];
; #pragma unroll
;     for (int j = 0; j < 4; ++j) { const f32x4 a = *(const f32x4*)(w + (size_t)j * C), b = *(const f32x4*)(w + (size_t)j * C + 4);
;         wv[j][0] = a[0]; wv[j][1] = a[1]; wv[j][2] = a[2]; wv[j][3] = a[3]; wv[j][4] = b[0]; wv[j][5] = b[1]; wv[j][6] = b[2]; wv[j][7] = b[3]; }
;     { const f32x4 a = *(const f32x4*)bias, b = *(const f32x4*)(bias + 4); bv[0] = a[0]; bv[1] = a[1]; bv[2] = a[2]; bv[3] = a[3]; bv[4] = b[0]; bv[5] = b[1]; bv[6] = b[2]; bv[7] = b[3]; }
; #pragma unroll
;     for (int i = 0; i < 7; ++i) unpack8(raw[i], x[i]);
; #pragma unroll
;     for (int t = 0; t < 4; ++t)
; #pragma unroll
;         for (int c = 0; c < 8; ++c) { float v = bv[c] + wv[0][c] * x[t][c] + wv[1][c] * x[t + 1][c] + wv[2][c] * x[t + 2][c] + wv[3][c] * x[t + 3][c]; out[t][c] = SILU ? silu_f(v) : v; }
	v_mul_f32_e32 v39, 0xbfb8aa3b, v35
	v_exp_f32_e32 v38, v38
	v_exp_f32_e32 v39, v39
	v_add_f32_e32 v38, 1.0, v38
	v_add_f32_e32 v39, 1.0, v39
	v_rcp_f32_e32 v38, v38
	v_rcp_f32_e32 v39, v39
	s_nop 0
	v_pk_mul_f32 v[34:35], v[34:35], v[38:39]
	v_pk_fma_f32 v[38:39], v[92:93], v[50:51], v[90:91]
	v_lshlrev_b32_e32 v90, 16, v56
	v_pk_fma_f32 v[38:39], v[96:97], v[46:47], v[38:39]
	v_and_b32_e32 v91, 0xffff0000, v56
	v_mul_f32_e32 v42, 0xbfb8aa3b, v38
	v_mul_f32_e32 v43, 0xbfb8aa3b, v39
	v_exp_f32_e32 v42, v42
	v_exp_f32_e32 v43, v43
	v_lshlrev_b32_e32 v56, 16, v57
	v_and_b32_e32 v57, 0xffff0000, v57
	v_add_f32_e32 v42, 1.0, v42
	v_add_f32_e32 v43, 1.0, v43
	v_rcp_f32_e32 v42, v42
	v_rcp_f32_e32 v43, v43
	s_nop 0
	v_pk_mul_f32 v[38:39], v[38:39], v[42:43]
	v_pk_fma_f32 v[42:43], v[88:89], v[50:51], v[86:87]
	v_pk_fma_f32 v[50:51], v[84:85], v[50:51], v[100:101]
	v_pk_fma_f32 v[42:43], v[92:93], v[46:47], v[42:43]
	v_pk_fma_f32 v[46:47], v[88:89], v[46:47], v[50:51]
	v_pk_fma_f32 v[42:43], v[96:97], v[58:59], v[42:43]
	v_pk_fma_f32 v[46:47], v[92:93], v[58:59], v[46:47]
	v_lshlrev_b32_e32 v84, 16, v52
	v_pk_fma_f32 v[46:47], v[96:97], v[54:55], v[46:47]
	v_lshlrev_b32_e32 v54, 16, v40
	v_mul_f32_e32 v50, 0xbfb8aa3b, v46
	v_mul_f32_e32 v51, 0xbfb8aa3b, v47
	v_exp_f32_e32 v50, v50
	v_exp_f32_e32 v51, v51
	v_and_b32_e32 v55, 0xffff0000, v40
	v_pk_fma_f32 v[92:93], v[62:63], v[54:55], v[78:79]
	v_add_f32_e32 v50, 1.0, v50
	v_add_f32_e32 v51, 1.0, v51
	v_rcp_f32_e32 v50, v50
	v_rcp_f32_e32 v51, v51
	v_pk_fma_f32 v[54:55], v[66:67], v[54:55], v[94:95]
	v_and_b32_e32 v85, 0xffff0000, v52
	v_mul_f32_e32 v86, 0xbfb8aa3b, v42
	v_pk_mul_f32 v[46:47], v[46:47], v[50:51]
	v_lshlrev_b32_e32 v50, 16, v44
	v_and_b32_e32 v51, 0xffff0000, v44
	v_pk_fma_f32 v[58:59], v[62:63], v[50:51], v[78:79]
	v_pk_fma_f32 v[92:93], v[66:67], v[50:51], v[92:93]
	v_pk_fma_f32 v[50:51], v[70:71], v[50:51], v[54:55]
	v_mul_f32_e32 v87, 0xbfb8aa3b, v43
	v_pk_fma_f32 v[50:51], v[74:75], v[84:85], v[50:51]
	v_exp_f32_e32 v86, v86
	v_mul_f32_e32 v36, 0xbfb8aa3b, v50
	v_exp_f32_e32 v36, v36
	v_exp_f32_e32 v87, v87
	v_add_f32_e32 v86, 1.0, v86
	v_rcp_f32_e32 v86, v86
	v_add_f32_e32 v36, 1.0, v36
	v_rcp_f32_e32 v54, v36
	v_mul_f32_e32 v36, 0xbfb8aa3b, v51
	v_exp_f32_e32 v36, v36
	v_add_f32_e32 v87, 1.0, v87
	v_rcp_f32_e32 v87, v87
	v_pk_fma_f32 v[58:59], v[66:67], v[84:85], v[58:59]
	v_add_f32_e32 v36, 1.0, v36
	v_rcp_f32_e32 v55, v36
	v_pk_mul_f32 v[42:43], v[42:43], v[86:87]
	v_lshlrev_b32_e32 v86, 16, v48
	v_and_b32_e32 v87, 0xffff0000, v48
	v_pk_mul_f32 v[50:51], v[50:51], v[54:55]
	v_pk_fma_f32 v[54:55], v[70:71], v[84:85], v[92:93]
	v_lshlrev_b32_e32 v88, 16, v60
	v_pk_fma_f32 v[54:55], v[74:75], v[86:87], v[54:55]
	v_and_b32_e32 v89, 0xffff0000, v60
	v_mul_f32_e32 v36, 0xbfb8aa3b, v54
	v_exp_f32_e32 v36, v36
	v_pk_fma_f32 v[58:59], v[70:71], v[86:87], v[58:59]
	v_pk_fma_f32 v[62:63], v[62:63], v[84:85], v[78:79]
	v_pk_fma_f32 v[58:59], v[74:75], v[88:89], v[58:59]
	v_add_f32_e32 v36, 1.0, v36
	v_rcp_f32_e32 v92, v36
	v_mul_f32_e32 v36, 0xbfb8aa3b, v55
	v_exp_f32_e32 v36, v36
	v_pk_fma_f32 v[62:63], v[66:67], v[86:87], v[62:63]
	v_lshlrev_b32_e32 v40, 16, v41
	v_pk_fma_f32 v[62:63], v[70:71], v[88:89], v[62:63]
	v_add_f32_e32 v36, 1.0, v36
	v_rcp_f32_e32 v93, v36
	v_mul_f32_e32 v36, 0xbfb8aa3b, v58
	v_exp_f32_e32 v36, v36
	v_pk_fma_f32 v[62:63], v[74:75], v[90:91], v[62:63]
	v_pk_mul_f32 v[54:55], v[54:55], v[92:93]
	v_and_b32_e32 v41, 0xffff0000, v41
	v_add_f32_e32 v36, 1.0, v36
	v_rcp_f32_e32 v92, v36
	v_mul_f32_e32 v36, 0xbfb8aa3b, v59
	v_exp_f32_e32 v36, v36
	v_lshlrev_b32_e32 v44, 16, v45
; #define LAS __attribute__((address_space(3)))
; DI float silu_f(float x) { return x * __builtin_amdgcn_rcpf(1.0f + __expf(-x)); }
; DI u32x4 pack8(const float (&v)[8]) { u32x4 w; w.x = pk2(v[0], v[1]); w.y = pk2(v[2], v[3]); w.z = pk2(v[4], v[5]); w.w = pk2(v[6], v[7]); return w; }
; template <bool SILU>
; DI void conv_compute(const u32x4 (&raw)[7], const float* w, int C, const float* bias, float (&out)[4][8]) {
;     float wv[4][8], bv[8], x[7][8];
; #pragma unroll
;     for (int j = 0; j < 4; ++j) { const f32x4 a = *(const f32x4*)(w + (size_t)j * C), b = *(const f32x4*)(w + (size_t)j * C + 4);
;         wv[j][0] = a[0]; wv[j][1] = a[1]; wv[j][2] = a[2]; wv[j][3] = a[3]; wv[j][4] = b[0]; wv[j][5] = b[1]; wv[j][6] = b[2]; wv[j][7] = b[3]; }
;     { const f32x4 a = *(const f32x4*)bias, b = *(const f32x4*)(bias + 4); bv[0] = a[0]; bv[1] = a[1]; bv[2] = a[2]; bv[3] = a[3]; bv[4] = b[0]; bv[5] = b[1]; bv[6] = b[2]; bv[7] = b[3]; }
; #pragma unroll
;     for (int i = 0; i < 7; ++i) unpack8(raw[i], x[i]);
; #pragma unroll
;     for (int t = 0; t < 4; ++t)
; #pragma unroll
;         for (int c = 0; c < 8; ++c) { float v = bv[c] + wv[0][c] * x[t][c] + wv[1][c] * x[t + 1][c] + wv[2][c] * x[t + 2][c] + wv[3][c] * x[t + 3][c]; out[t][c] = SILU ? silu_f(v) : v; }
; DI void ssd_pass2(LAS unsigned char* lds, const Args& a, const LayerP& P, int unit, int wv) {
;     ...
;         { float o[4][8]; conv_compute<true>(rawB, P.ssd_cw + 256 + g * 128 + cv * 8, 768, P.ssd_cb + 256 + g * 128 + cv * 8, o);
; #pragma unroll
;           for (int t = 0; t < 4; ++t) *(LAS u32x4*)(R1 + (t0 + t) * PT + cv * 8) = pack8(o[t]); }
;         u32x4 rawX[7]; conv_load(Hb + C_XBC + g * 128 + cv * 8, c * 128 + t0, rawX);
	v_and_b32_e32 v45, 0xffff0000, v45
	v_lshlrev_b32_e32 v52, 16, v53
	v_add_f32_e32 v36, 1.0, v36
	v_rcp_f32_e32 v93, v36
	v_mul_f32_e32 v36, 0xbfb8aa3b, v62
	v_exp_f32_e32 v36, v36
	v_and_b32_e32 v53, 0xffff0000, v53
	v_pk_fma_f32 v[70:71], v[64:65], v[40:41], v[80:81]
	v_lshlrev_b32_e32 v48, 16, v49
	v_add_f32_e32 v36, 1.0, v36
	v_rcp_f32_e32 v66, v36
	v_mul_f32_e32 v36, 0xbfb8aa3b, v63
	v_exp_f32_e32 v36, v36
	v_pk_fma_f32 v[70:71], v[68:69], v[44:45], v[70:71]
	v_and_b32_e32 v49, 0xffff0000, v49
	v_lshlrev_b32_e32 v60, 16, v61
	v_add_f32_e32 v36, 1.0, v36
	v_rcp_f32_e32 v67, v36
	v_lshlrev_b32_e32 v36, 16, v37
	v_and_b32_e32 v37, 0xffff0000, v37
	v_pk_fma_f32 v[36:37], v[64:65], v[36:37], v[80:81]
	v_pk_mul_f32 v[62:63], v[62:63], v[66:67]
	v_pk_fma_f32 v[36:37], v[68:69], v[40:41], v[36:37]
	v_pk_fma_f32 v[66:67], v[64:65], v[44:45], v[80:81]
	v_pk_fma_f32 v[36:37], v[72:73], v[44:45], v[36:37]
	v_and_b32_e32 v61, 0xffff0000, v61
	v_pk_fma_f32 v[36:37], v[76:77], v[52:53], v[36:37]
	v_pk_mul_f32 v[58:59], v[58:59], v[92:93]
	v_mul_f32_e32 v40, 0xbfb8aa3b, v36
	v_mul_f32_e32 v41, 0xbfb8aa3b, v37
	v_exp_f32_e32 v40, v40
	v_exp_f32_e32 v41, v41
	v_cvt_pk_bf16_f32 v50, v50, v51
	v_add_f32_e32 v40, 1.0, v40
	v_add_f32_e32 v41, 1.0, v41
	v_rcp_f32_e32 v40, v40
	v_rcp_f32_e32 v41, v41
	s_nop 0
	v_pk_mul_f32 v[36:37], v[36:37], v[40:41]
	v_pk_fma_f32 v[40:41], v[72:73], v[52:53], v[70:71]
	v_cvt_pk_bf16_f32 v51, v36, v37
	v_pk_fma_f32 v[40:41], v[76:77], v[48:49], v[40:41]
	v_cvt_pk_bf16_f32 v36, v54, v55
	v_mul_f32_e32 v44, 0xbfb8aa3b, v40
	v_mul_f32_e32 v45, 0xbfb8aa3b, v41
	v_exp_f32_e32 v44, v44
	v_exp_f32_e32 v45, v45
	v_add_f32_e32 v44, 1.0, v44
	v_add_f32_e32 v45, 1.0, v45
	v_rcp_f32_e32 v44, v44
	v_rcp_f32_e32 v45, v45
	s_nop 0
	v_pk_mul_f32 v[40:41], v[40:41], v[44:45]
	v_pk_fma_f32 v[44:45], v[68:69], v[52:53], v[66:67]
	v_pk_fma_f32 v[52:53], v[64:65], v[52:53], v[80:81]
	v_pk_fma_f32 v[44:45], v[72:73], v[48:49], v[44:45]
	v_pk_fma_f32 v[48:49], v[68:69], v[48:49], v[52:53]
	v_pk_fma_f32 v[44:45], v[76:77], v[60:61], v[44:45]
	v_pk_fma_f32 v[48:49], v[72:73], v[60:61], v[48:49]
	v_mul_f32_e32 v66, 0xbfb8aa3b, v44
	v_pk_fma_f32 v[48:49], v[76:77], v[56:57], v[48:49]
	v_mul_f32_e32 v67, 0xbfb8aa3b, v45
	v_mul_f32_e32 v52, 0xbfb8aa3b, v48
	v_mul_f32_e32 v53, 0xbfb8aa3b, v49
	v_exp_f32_e32 v66, v66
	v_exp_f32_e32 v67, v67
	v_exp_f32_e32 v52, v52
	v_exp_f32_e32 v53, v53
	v_add_f32_e32 v66, 1.0, v66
	v_add_f32_e32 v67, 1.0, v67
	v_add_f32_e32 v52, 1.0, v52
	v_add_f32_e32 v53, 1.0, v53
	v_rcp_f32_e32 v66, v66
	v_rcp_f32_e32 v67, v67
	v_rcp_f32_e32 v52, v52
	v_rcp_f32_e32 v53, v53
	v_cvt_pk_bf16_f32 v37, v40, v41
	v_pk_mul_f32 v[44:45], v[44:45], v[66:67]
	v_pk_mul_f32 v[52:53], v[48:49], v[52:53]
	v_cvt_pk_bf16_f32 v49, v34, v35
	v_cvt_pk_bf16_f32 v34, v114, v115
	v_cvt_pk_bf16_f32 v35, v38, v39
	ds_write_b128 v132, v[34:37] offset:35088
	v_cvt_pk_bf16_f32 v34, v116, v117
	v_cvt_pk_bf16_f32 v35, v42, v43
	v_cvt_pk_bf16_f32 v36, v58, v59
	v_cvt_pk_bf16_f32 v37, v44, v45
	ds_write_b128 v132, v[34:37] offset:35360
	v_cvt_pk_bf16_f32 v34, v82, v83
	v_cvt_pk_bf16_f32 v35, v46, v47
	v_cvt_pk_bf16_f32 v36, v62, v63
	v_cvt_pk_bf16_f32 v37, v52, v53
	v_cvt_pk_bf16_f32 v48, v112, v113
	ds_write_b128 v133, v[34:37] offset:34816
	v_mov_b32_e32 v38, 0
	v_mov_b32_e32 v34, 0
	v_mov_b32_e32 v35, 0
	v_mov_b32_e32 v36, 0
	v_mov_b32_e32 v37, 0
	ds_write_b128 v132, v[48:51] offset:34816
	s_and_saveexec_b64 s[2:3], s[16:17]
	s_cbranch_execz .LBB0_1405
	v_mad_u64_u32 v[34:35], s[16:17], v126, s73, v[106:107]
	global_load_dwordx4 v[34:37], v[34:35], off offset:1312

; #define LAS __attribute__((address_space(3)))
; DI unsigned pk2(float lo, float hi) { const f32x2 v = {lo, hi}; const hwbf16x2 b = __builtin_convertvector(v, hwbf16x2); return __builtin_bit_cast(unsigned, b); }
; DI float silu_f(float x) { return x * __builtin_amdgcn_rcpf(1.0f + __expf(-x)); }
; template <bool SILU>
; DI void conv_compute(const u32x4 (&raw)[7], const float* w, int C, const float* bias, float (&out)[4][8]) {
;     float wv[4][8], bv[8], x[7][8];
; #pragma unroll
;     for (int j = 0; j < 4; ++j) { const f32x4 a = *(const f32x4*)(w + (size_t)j * C), b = *(const f32x4*)(w + (size_t)j * C + 4);
;         wv[j][0] = a[0]; wv[j][1] = a[1]; wv[j][2] = a[2]; wv[j][3] = a[3]; wv[j][4] = b[0]; wv[j][5] = b[1]; wv[j][6] = b[2]; wv[j][7] = b[3]; }
;     { const f32x4 a = *(const f32x4*)bias, b = *(const f32x4*)(bias + 4); bv[0] = a[0]; bv[1] = a[1]; bv[2] = a[2]; bv[3] = a[3]; bv[4] = b[0]; bv[5] = b[1]; bv[6] = b[2]; bv[7] = b[3]; }
; #pragma unroll
;     for (int i = 0; i < 7; ++i) unpack8(raw[i], x[i]);
; #pragma unroll
;     for (int t = 0; t < 4; ++t)
; #pragma unroll
;         for (int c = 0; c < 8; ++c) { float v = bv[c] + wv[0][c] * x[t][c] + wv[1][c] * x[t + 1][c] + wv[2][c] * x[t + 2][c] + wv[3][c] * x[t + 3][c]; out[t][c] = SILU ? silu_f(v) : v; }
; DI void ssd_pass2(LAS unsigned char* lds, const Args& a, const LayerP& P, int unit, int wv) {
;     ...
;         __syncthreads();
;         { float o[4][8]; conv_compute<true>(rawX, P.ssd_cw + g * 128 + cv * 8, 768, P.ssd_cb + g * 128 + cv * 8, o);
; #pragma unroll
;           for (int k = 0; k < 8; ++k) { u32x2 v; v.x = pk2(o[0][k], o[1][k]); v.y = pk2(o[2][k], o[3][k]); *(LAS u32x2*)(R1 + ((cv >> 3) * 64 + (cv & 7) * 8 + k) * PT + t0) = v; } }
.LBB0_1485:
	s_waitcnt lgkmcnt(0)
	global_load_dwordx4 v[82:85], v[102:103], off
	global_load_dwordx4 v[90:93], v[108:109], off
	global_load_dwordx4 v[94:97], v[102:103], off offset:3072
	s_movk_i32 s2, 0x1000
	v_add_co_u32_e32 v62, vcc, s2, v102
	s_mov_b64 s[2:3], 0x2400
	s_nop 0
	v_addc_co_u32_e32 v63, vcc, 0, v103, vcc
	global_load_dwordx4 v[98:101], v[62:63], off offset:2048
	global_load_dwordx4 v[114:117], v[104:105], off offset:1024
	global_load_dwordx4 v[66:69], v[102:103], off offset:16
	s_nop 0
	global_load_dwordx4 v[62:65], v[102:103], off offset:3088
	global_load_dwordx4 v[70:73], v[108:109], off offset:16
	v_lshl_add_u64 v[74:75], v[102:103], 0, s[64:65]
	v_lshl_add_u64 v[76:77], v[102:103], 0, s[2:3]
	global_load_dwordx4 v[78:81], v[74:75], off offset:16
	s_nop 0
	global_load_dwordx4 v[74:77], v[76:77], off offset:16
	s_barrier
	s_waitcnt vmcnt(10)
	v_lshlrev_b32_e32 v87, 16, v46
	v_lshlrev_b32_e32 v86, 16, v42
	v_lshlrev_b32_e32 v109, 16, v38
	v_lshlrev_b32_e32 v108, 16, v34
	v_and_b32_e32 v127, 0xffff0000, v46
	v_and_b32_e32 v126, 0xffff0000, v42
	v_and_b32_e32 v135, 0xffff0000, v38
	v_and_b32_e32 v134, 0xffff0000, v34
	v_pk_mov_b32 v[138:139], v[108:109], v[86:87] op_sel:[1,0]
	v_pk_mov_b32 v[140:141], v[134:135], v[126:127] op_sel:[1,0]
	v_lshlrev_b32_e32 v89, 16, v54
	v_and_b32_e32 v129, 0xffff0000, v54
	v_mov_b32_e32 v88, v87
	v_mov_b32_e32 v128, v127
	v_and_b32_e32 v131, 0xffff0000, v50
	v_mov_b32_e32 v130, v129
	v_lshlrev_b32_e32 v103, 16, v50
	v_and_b32_e32 v133, 0xffff0000, v58
	v_mov_b32_e32 v102, v89
	v_mov_b32_e32 v132, v131
	v_lshlrev_b32_e32 v105, 16, v58
	v_mov_b32_e32 v104, v103
	v_lshlrev_b32_e32 v136, 16, v43
	v_lshlrev_b32_e32 v137, 16, v47
	v_and_b32_e32 v47, 0xffff0000, v47
	s_add_i32 s2, s58, s61
	s_mov_b32 s3, s59
	s_lshl_b64 s[16:17], s[2:3], 2
	s_add_u32 s16, s90, s16
	s_addc_u32 s17, s91, s17
	v_pk_mul_f32 v[8:9], v[8:9], v[110:111] op_sel_hi:[1,0]
	v_pk_mul_f32 v[6:7], v[6:7], v[110:111] op_sel_hi:[1,0]
	v_pk_mul_f32 v[4:5], v[4:5], v[110:111] op_sel_hi:[1,0]
	v_pk_mul_f32 v[2:3], v[2:3], v[110:111] op_sel_hi:[1,0]
	s_lshl_b32 s58, s2, 6
	s_movk_i32 s3, 0xffe0
	s_waitcnt vmcnt(8)
	v_pk_fma_f32 v[108:109], v[82:83], v[108:109], v[90:91] op_sel_hi:[0,1,0]
	v_pk_fma_f32 v[134:135], v[82:83], v[134:135], v[90:91] op_sel:[1,0,1]
	v_pk_fma_f32 v[142:143], v[82:83], v[86:87], v[90:91] op_sel_hi:[0,1,0]
	v_pk_fma_f32 v[82:83], v[82:83], v[126:127], v[90:91] op_sel:[1,0,1]
	s_waitcnt vmcnt(7)
	v_pk_fma_f32 v[90:91], v[94:95], v[138:139], v[108:109] op_sel_hi:[0,1,1]
	v_pk_fma_f32 v[134:135], v[94:95], v[140:141], v[134:135] op_sel:[1,0,0]
	v_pk_fma_f32 v[108:109], v[94:95], v[88:89], v[142:143] op_sel_hi:[0,1,1]
	v_pk_fma_f32 v[82:83], v[94:95], v[128:129], v[82:83] op_sel:[1,0,0]
	s_waitcnt vmcnt(6)
	v_pk_fma_f32 v[86:87], v[98:99], v[86:87], v[90:91] op_sel_hi:[0,1,1]
	v_pk_fma_f32 v[94:95], v[98:99], v[126:127], v[134:135] op_sel:[1,0,0]
	v_pk_fma_f32 v[82:83], v[98:99], v[130:131], v[82:83] op_sel:[1,0,0]
	s_waitcnt vmcnt(5)
	v_pk_fma_f32 v[86:87], v[114:115], v[88:89], v[86:87] op_sel_hi:[0,1,1]
	v_pk_fma_f32 v[94:95], v[114:115], v[128:129], v[94:95] op_sel:[1,0,0]
	v_pk_fma_f32 v[90:91], v[98:99], v[102:103], v[108:109] op_sel_hi:[0,1,1]
	v_pk_fma_f32 v[98:99], v[114:115], v[132:133], v[82:83] op_sel:[1,0,0]
	v_mul_f32_e32 v0, 0xbfb8aa3b, v86
	v_mul_f32_e32 v34, 0xbfb8aa3b, v87
	v_mul_f32_e32 v46, 0xbfb8aa3b, v94
	v_mul_f32_e32 v50, 0xbfb8aa3b, v95
	v_mul_f32_e32 v54, 0xbfb8aa3b, v98
	v_mul_f32_e32 v58, 0xbfb8aa3b, v99
	v_exp_f32_e32 v0, v0
	v_exp_f32_e32 v34, v34
	v_exp_f32_e32 v46, v46
	v_exp_f32_e32 v50, v50
	v_exp_f32_e32 v54, v54
	v_exp_f32_e32 v58, v58
	v_add_f32_e32 v0, 1.0, v0
	v_add_f32_e32 v34, 1.0, v34
	v_add_f32_e32 v46, 1.0, v46
	v_add_f32_e32 v50, 1.0, v50
	v_pk_fma_f32 v[90:91], v[114:115], v[104:105], v[90:91] op_sel_hi:[0,1,1]
	v_add_f32_e32 v54, 1.0, v54
	v_add_f32_e32 v58, 1.0, v58
	v_rcp_f32_e32 v82, v0
	v_rcp_f32_e32 v83, v34
	v_rcp_f32_e32 v104, v46
	v_rcp_f32_e32 v105, v50
	v_rcp_f32_e32 v108, v54
	v_rcp_f32_e32 v109, v58
	v_mul_f32_e32 v38, 0xbfb8aa3b, v90
	v_mul_f32_e32 v42, 0xbfb8aa3b, v91
	v_exp_f32_e32 v38, v38
	v_exp_f32_e32 v42, v42
	v_pk_mul_f32 v[88:89], v[86:87], v[82:83]
	v_pk_mul_f32 v[82:83], v[94:95], v[104:105]
	v_lshlrev_b32_e32 v104, 16, v35
	v_lshlrev_b32_e32 v105, 16, v39
	v_pk_mul_f32 v[86:87], v[98:99], v[108:109]
	v_pk_fma_f32 v[108:109], v[84:85], v[104:105], v[92:93] op_sel_hi:[0,1,0]
	v_pk_mov_b32 v[104:105], v[104:105], v[136:137] op_sel:[1,0]
	v_lshlrev_b32_e32 v95, 16, v55
	v_pk_fma_f32 v[104:105], v[96:97], v[104:105], v[108:109] op_sel_hi:[0,1,1]
	v_mov_b32_e32 v94, v137
	v_pk_fma_f32 v[104:105], v[100:101], v[136:137], v[104:105] op_sel_hi:[0,1,1]
	v_add_f32_e32 v38, 1.0, v38
	v_add_f32_e32 v42, 1.0, v42
	v_pk_fma_f32 v[104:105], v[116:117], v[94:95], v[104:105] op_sel_hi:[0,1,1]
	v_rcp_f32_e32 v102, v38
	v_rcp_f32_e32 v103, v42
	v_mul_f32_e32 v0, 0xbfb8aa3b, v104
	v_exp_f32_e32 v0, v0
	v_mul_f32_e32 v34, 0xbfb8aa3b, v105
	v_exp_f32_e32 v34, v34
	v_pk_fma_f32 v[114:115], v[84:85], v[136:137], v[92:93] op_sel_hi:[0,1,0]
	v_lshlrev_b32_e32 v99, 16, v51
	v_mov_b32_e32 v98, v95
	v_pk_fma_f32 v[94:95], v[96:97], v[94:95], v[114:115] op_sel_hi:[0,1,1]
	v_pk_mul_f32 v[90:91], v[90:91], v[102:103]
	v_lshlrev_b32_e32 v103, 16, v59
	v_mov_b32_e32 v102, v99
	v_pk_fma_f32 v[94:95], v[100:101], v[98:99], v[94:95] op_sel_hi:[0,1,1]
	v_add_f32_e32 v0, 1.0, v0
	v_pk_fma_f32 v[94:95], v[116:117], v[102:103], v[94:95] op_sel_hi:[0,1,1]
	v_rcp_f32_e32 v108, v0
	v_add_f32_e32 v0, 1.0, v34
	v_mul_f32_e32 v34, 0xbfb8aa3b, v94
	v_exp_f32_e32 v34, v34
; DI float silu_f(float x) { return x * __builtin_amdgcn_rcpf(1.0f + __expf(-x)); }
; template <bool SILU>
; DI void conv_compute(const u32x4 (&raw)[7], const float* w, int C, const float* bias, float (&out)[4][8]) {
;     float wv[4][8], bv[8], x[7][8];
; #pragma unroll
;     for (int j = 0; j < 4; ++j) { const f32x4 a = *(const f32x4*)(w + (size_t)j * C), b = *(const f32x4*)(w + (size_t)j * C + 4);
;         wv[j][0] = a[0]; wv[j][1] = a[1]; wv[j][2] = a[2]; wv[j][3] = a[3]; wv[j][4] = b[0]; wv[j][5] = b[1]; wv[j][6] = b[2]; wv[j][7] = b[3]; }
;     { const f32x4 a = *(const f32x4*)bias, b = *(const f32x4*)(bias + 4); bv[0] = a[0]; bv[1] = a[1]; bv[2] = a[2]; bv[3] = a[3]; bv[4] = b[0]; bv[5] = b[1]; bv[6] = b[2]; bv[7] = b[3]; }
; #pragma unroll
;     for (int i = 0; i < 7; ++i) unpack8(raw[i], x[i]);
; #pragma unroll
;     for (int t = 0; t < 4; ++t)
; #pragma unroll
;         for (int c = 0; c < 8; ++c) { float v = bv[c] + wv[0][c] * x[t][c] + wv[1][c] * x[t + 1][c] + wv[2][c] * x[t + 2][c] + wv[3][c] * x[t + 3][c]; out[t][c] = SILU ? silu_f(v) : v; }
	v_mul_f32_e32 v38, 0xbfb8aa3b, v95
	v_exp_f32_e32 v38, v38
	v_rcp_f32_e32 v109, v0
	v_add_f32_e32 v0, 1.0, v34
	v_rcp_f32_e32 v98, v0
	v_add_f32_e32 v0, 1.0, v38
	v_rcp_f32_e32 v99, v0
	v_and_b32_e32 v46, 0xffff0000, v43
	v_and_b32_e32 v39, 0xffff0000, v39
	v_and_b32_e32 v38, 0xffff0000, v35
	v_mov_b32_e32 v0, v85
	v_mov_b32_e32 v34, v93
	v_and_b32_e32 v43, 0xffff0000, v55
	v_and_b32_e32 v55, 0xffff0000, v59
	v_pk_fma_f32 v[58:59], v[0:1], v[38:39], v[34:35] op_sel_hi:[0,1,0]
	v_mov_b32_e32 v84, v97
	v_pk_mov_b32 v[38:39], v[38:39], v[46:47] op_sel:[1,0]
	v_mov_b32_e32 v42, v47
	v_pk_fma_f32 v[38:39], v[84:85], v[38:39], v[58:59] op_sel_hi:[0,1,1]
	v_mov_b32_e32 v58, v101
	v_pk_fma_f32 v[38:39], v[58:59], v[46:47], v[38:39] op_sel_hi:[0,1,1]
	v_mov_b32_e32 v92, v117
	v_pk_fma_f32 v[96:97], v[92:93], v[42:43], v[38:39] op_sel_hi:[0,1,1]
	v_mul_f32_e32 v35, 0xbfb8aa3b, v96
	v_exp_f32_e32 v35, v35
	v_and_b32_e32 v51, 0xffff0000, v51
	v_mov_b32_e32 v50, v43
	v_mov_b32_e32 v54, v51
	v_add_f32_e32 v35, 1.0, v35
	v_rcp_f32_e32 v100, v35
	v_pk_fma_f32 v[34:35], v[0:1], v[46:47], v[34:35] op_sel_hi:[0,1,0]
	v_pk_fma_f32 v[34:35], v[84:85], v[42:43], v[34:35] op_sel_hi:[0,1,1]
	v_pk_fma_f32 v[34:35], v[58:59], v[50:51], v[34:35] op_sel_hi:[0,1,1]
	v_pk_fma_f32 v[46:47], v[92:93], v[54:55], v[34:35] op_sel_hi:[0,1,1]
	v_mul_f32_e32 v0, 0xbfb8aa3b, v46
	v_exp_f32_e32 v0, v0
	v_mul_f32_e32 v34, 0xbfb8aa3b, v47
	v_exp_f32_e32 v34, v34
	v_mul_f32_e32 v38, 0xbfb8aa3b, v97
	v_add_f32_e32 v0, 1.0, v0
	v_rcp_f32_e32 v50, v0
	v_add_f32_e32 v0, 1.0, v34
	v_rcp_f32_e32 v51, v0
	v_lshlrev_b32_e32 v93, 16, v40
	v_lshlrev_b32_e32 v92, 16, v36
	v_exp_f32_e32 v38, v38
	v_pk_mul_f32 v[46:47], v[46:47], v[50:51]
	v_lshlrev_b32_e32 v51, 16, v48
	v_lshlrev_b32_e32 v50, 16, v44
	v_pk_mul_f32 v[42:43], v[94:95], v[98:99]
	s_waitcnt vmcnt(2)
	v_pk_fma_f32 v[94:95], v[66:67], v[92:93], v[70:71] op_sel_hi:[0,1,0]
	v_pk_mov_b32 v[92:93], v[92:93], v[50:51] op_sel:[1,0]
	v_lshlrev_b32_e32 v55, 16, v56
	v_pk_fma_f32 v[92:93], v[62:63], v[92:93], v[94:95] op_sel_hi:[0,1,1]
	v_mov_b32_e32 v54, v51
	s_waitcnt vmcnt(1)
	v_pk_fma_f32 v[92:93], v[78:79], v[50:51], v[92:93] op_sel_hi:[0,1,1]
	s_waitcnt vmcnt(0)
	v_pk_fma_f32 v[92:93], v[74:75], v[54:55], v[92:93] op_sel_hi:[0,1,1]
	v_pk_fma_f32 v[50:51], v[66:67], v[50:51], v[70:71] op_sel_hi:[0,1,0]
	v_add_f32_e32 v38, 1.0, v38
	v_lshlrev_b32_e32 v59, 16, v52
	v_mov_b32_e32 v58, v55
	v_mul_f32_e32 v84, 0xbfb8aa3b, v93
	v_pk_fma_f32 v[50:51], v[62:63], v[54:55], v[50:51] op_sel_hi:[0,1,1]
	v_rcp_f32_e32 v101, v38
	v_lshlrev_b32_e32 v85, 16, v60
	v_mul_f32_e32 v0, 0xbfb8aa3b, v92
	v_exp_f32_e32 v95, v84
	v_mov_b32_e32 v84, v59
	v_pk_fma_f32 v[50:51], v[78:79], v[58:59], v[50:51] op_sel_hi:[0,1,1]
	v_exp_f32_e32 v0, v0
	v_pk_fma_f32 v[50:51], v[74:75], v[84:85], v[50:51] op_sel_hi:[0,1,1]
	v_mul_f32_e32 v54, 0xbfb8aa3b, v50
	v_exp_f32_e32 v54, v54
	v_mul_f32_e32 v55, 0xbfb8aa3b, v51
	v_pk_mul_f32 v[34:35], v[96:97], v[100:101]
	v_exp_f32_e32 v55, v55
	v_and_b32_e32 v59, 0xffff0000, v48
	v_and_b32_e32 v58, 0xffff0000, v44
	v_and_b32_e32 v101, 0xffff0000, v40
	v_and_b32_e32 v100, 0xffff0000, v36
	v_add_f32_e32 v0, 1.0, v0
	v_pk_fma_f32 v[102:103], v[66:67], v[100:101], v[70:71] op_sel:[1,0,1]
	v_pk_mov_b32 v[100:101], v[100:101], v[58:59] op_sel:[1,0]
	v_rcp_f32_e32 v94, v0
	v_add_f32_e32 v0, 1.0, v95
	v_pk_fma_f32 v[100:101], v[62:63], v[100:101], v[102:103] op_sel:[1,0,0]
	v_rcp_f32_e32 v95, v0
	v_add_f32_e32 v0, 1.0, v54
	v_and_b32_e32 v85, 0xffff0000, v56
	v_mov_b32_e32 v84, v59
	v_pk_fma_f32 v[100:101], v[78:79], v[58:59], v[100:101] op_sel:[1,0,0]
	v_rcp_f32_e32 v54, v0
	v_add_f32_e32 v0, 1.0, v55
	v_pk_fma_f32 v[100:101], v[74:75], v[84:85], v[100:101] op_sel:[1,0,0]
	v_rcp_f32_e32 v55, v0
	v_mul_f32_e32 v0, 0xbfb8aa3b, v100
	v_exp_f32_e32 v0, v0
	v_mul_f32_e32 v36, 0xbfb8aa3b, v101
	v_exp_f32_e32 v36, v36
	v_pk_fma_f32 v[58:59], v[66:67], v[58:59], v[70:71] op_sel:[1,0,1]
	v_and_b32_e32 v97, 0xffff0000, v52
	v_mov_b32_e32 v96, v85
	v_pk_fma_f32 v[58:59], v[62:63], v[84:85], v[58:59] op_sel:[1,0,0]
	v_and_b32_e32 v99, 0xffff0000, v60
	v_mov_b32_e32 v98, v97
	v_pk_fma_f32 v[58:59], v[78:79], v[96:97], v[58:59] op_sel:[1,0,0]
	v_add_f32_e32 v0, 1.0, v0
	v_pk_fma_f32 v[58:59], v[74:75], v[98:99], v[58:59] op_sel:[1,0,0]
	v_rcp_f32_e32 v102, v0
	v_add_f32_e32 v0, 1.0, v36
	v_mul_f32_e32 v36, 0xbfb8aa3b, v58
	v_exp_f32_e32 v36, v36
	v_mul_f32_e32 v40, 0xbfb8aa3b, v59
	v_exp_f32_e32 v40, v40
	v_rcp_f32_e32 v103, v0
	v_add_f32_e32 v0, 1.0, v36
	v_rcp_f32_e32 v62, v0
	v_add_f32_e32 v0, 1.0, v40
	v_rcp_f32_e32 v63, v0
	v_lshlrev_b32_e32 v84, 16, v37
	v_lshlrev_b32_e32 v85, 16, v41
	v_pk_mul_f32 v[66:67], v[92:93], v[94:95]
	v_pk_mul_f32 v[58:59], v[58:59], v[62:63]
	v_lshlrev_b32_e32 v62, 16, v45
	v_lshlrev_b32_e32 v63, 16, v49
	v_pk_fma_f32 v[92:93], v[68:69], v[84:85], v[72:73] op_sel_hi:[0,1,0]
	v_pk_mov_b32 v[84:85], v[84:85], v[62:63] op_sel:[1,0]
	v_lshlrev_b32_e32 v71, 16, v57
	v_pk_fma_f32 v[84:85], v[64:65], v[84:85], v[92:93] op_sel_hi:[0,1,1]
	v_mov_b32_e32 v70, v63
	v_pk_fma_f32 v[84:85], v[80:81], v[62:63], v[84:85] op_sel_hi:[0,1,1]
	v_pk_fma_f32 v[84:85], v[76:77], v[70:71], v[84:85] op_sel_hi:[0,1,1]
	v_mul_f32_e32 v0, 0xbfb8aa3b, v84
	v_exp_f32_e32 v0, v0
; #define LAS __attribute__((address_space(3)))
; DI unsigned pk2(float lo, float hi) { const f32x2 v = {lo, hi}; const hwbf16x2 b = __builtin_convertvector(v, hwbf16x2); return __builtin_bit_cast(unsigned, b); }
; DI void ssd_pass2(LAS unsigned char* lds, const Args& a, const LayerP& P, int unit, int wv) {
;     ...
;         { float o[4][8]; conv_compute<true>(rawX, P.ssd_cw + g * 128 + cv * 8, 768, P.ssd_cb + g * 128 + cv * 8, o);
; #pragma unroll
;           for (int k = 0; k < 8; ++k) { u32x2 v; v.x = pk2(o[0][k], o[1][k]); v.y = pk2(o[2][k], o[3][k]); *(LAS u32x2*)(R1 + ((cv >> 3) * 64 + (cv & 7) * 8 + k) * PT + t0) = v; } }
;         __syncthreads();
;         const int h = 2 * g + hh; const float dsk = P.ssd_d[h];
;         u32x2 zr[2][4];
; #pragma unroll
;         for (int ni = 0; ni < 2; ++ni)
; #pragma unroll
;             for (int mi = 0; mi < 4; ++mi) zr[ni][mi] = *(const u32x2*)(Hg + (size_t)(row0 + lr + ni * 16 + r) * HP + C_Z + h * 64 + mi * 16 + 4 * q);
	v_mul_f32_e32 v36, 0xbfb8aa3b, v85
	v_exp_f32_e32 v36, v36
	v_pk_fma_f32 v[62:63], v[68:69], v[62:63], v[72:73] op_sel_hi:[0,1,0]
	v_lshlrev_b32_e32 v75, 16, v53
	v_mov_b32_e32 v74, v71
	v_pk_fma_f32 v[62:63], v[64:65], v[70:71], v[62:63] op_sel_hi:[0,1,1]
	v_lshlrev_b32_e32 v79, 16, v61
	v_mov_b32_e32 v78, v75
	v_pk_fma_f32 v[62:63], v[80:81], v[74:75], v[62:63] op_sel_hi:[0,1,1]
	v_add_f32_e32 v0, 1.0, v0
	v_pk_fma_f32 v[62:63], v[76:77], v[78:79], v[62:63] op_sel_hi:[0,1,1]
	v_rcp_f32_e32 v92, v0
	v_add_f32_e32 v0, 1.0, v36
	v_mul_f32_e32 v36, 0xbfb8aa3b, v62
	v_exp_f32_e32 v36, v36
	v_mul_f32_e32 v40, 0xbfb8aa3b, v63
	v_exp_f32_e32 v40, v40
	v_rcp_f32_e32 v93, v0
	v_add_f32_e32 v0, 1.0, v36
	v_rcp_f32_e32 v70, v0
	v_add_f32_e32 v0, 1.0, v40
	v_rcp_f32_e32 v71, v0
	v_and_b32_e32 v49, 0xffff0000, v49
	v_and_b32_e32 v48, 0xffff0000, v45
	v_and_b32_e32 v41, 0xffff0000, v41
	v_and_b32_e32 v40, 0xffff0000, v37
	v_mov_b32_e32 v0, v69
	v_mov_b32_e32 v36, v73
	v_and_b32_e32 v45, 0xffff0000, v57
	v_and_b32_e32 v57, 0xffff0000, v61
	v_pk_fma_f32 v[60:61], v[0:1], v[40:41], v[36:37] op_sel_hi:[0,1,0]
	v_mov_b32_e32 v64, v65
	v_pk_mov_b32 v[40:41], v[40:41], v[48:49] op_sel:[1,0]
	v_mov_b32_e32 v44, v49
	v_pk_fma_f32 v[40:41], v[64:65], v[40:41], v[60:61] op_sel_hi:[0,1,1]
	v_mov_b32_e32 v60, v81
	v_pk_fma_f32 v[40:41], v[60:61], v[48:49], v[40:41] op_sel_hi:[0,1,1]
	v_mov_b32_e32 v68, v77
	v_pk_fma_f32 v[40:41], v[68:69], v[44:45], v[40:41] op_sel_hi:[0,1,1]
	v_mul_f32_e32 v37, 0xbfb8aa3b, v40
	v_exp_f32_e32 v37, v37
	v_mul_f32_e32 v56, 0xbfb8aa3b, v41
	v_exp_f32_e32 v61, v56
	v_and_b32_e32 v53, 0xffff0000, v53
	v_add_f32_e32 v37, 1.0, v37
	v_rcp_f32_e32 v72, v37
	v_pk_fma_f32 v[36:37], v[0:1], v[48:49], v[36:37] op_sel_hi:[0,1,0]
	v_mov_b32_e32 v52, v45
	v_add_f32_e32 v61, 1.0, v61
	v_pk_fma_f32 v[36:37], v[64:65], v[44:45], v[36:37] op_sel_hi:[0,1,1]
	v_mov_b32_e32 v56, v53
	v_pk_fma_f32 v[36:37], v[60:61], v[52:53], v[36:37] op_sel_hi:[0,1,1]
	v_pk_fma_f32 v[36:37], v[68:69], v[56:57], v[36:37] op_sel_hi:[0,1,1]
	v_mul_f32_e32 v0, 0xbfb8aa3b, v36
	v_exp_f32_e32 v0, v0
	v_mul_f32_e32 v44, 0xbfb8aa3b, v37
	v_exp_f32_e32 v45, v44
	v_rcp_f32_e32 v73, v61
	v_add_f32_e32 v0, 1.0, v0
	v_rcp_f32_e32 v44, v0
	v_add_f32_e32 v0, 1.0, v45
	v_rcp_f32_e32 v45, v0
	v_lshlrev_b32_e32 v0, 3, v119
	v_and_b32_e32 v0, 56, v0
	v_and_or_b32 v0, v122, 64, v0
	v_lshlrev_b32_e32 v56, 1, v121
	v_mul_u32_u24_e32 v0, 0x110, v0
	v_pk_mul_f32 v[38:39], v[104:105], v[108:109]
	v_add3_u32 v0, 0, v56, v0
	v_pk_mul_f32 v[50:51], v[50:51], v[54:55]
	v_pk_mul_f32 v[54:55], v[100:101], v[102:103]
	v_add_u32_e32 v0, 0x8800, v0
	v_cvt_pk_bf16_f32 v38, v38, v39
	v_cvt_pk_bf16_f32 v39, v42, v43
	v_cvt_pk_bf16_f32 v34, v34, v35
	v_cvt_pk_bf16_f32 v35, v46, v47
	v_pk_mul_f32 v[48:49], v[84:85], v[92:93]
	v_pk_mul_f32 v[52:53], v[62:63], v[70:71]
	v_pk_mul_f32 v[40:41], v[40:41], v[72:73]
	v_pk_mul_f32 v[36:37], v[36:37], v[44:45]
	ds_write2_b64 v0, v[38:39], v[34:35] offset0:68 offset1:102
	v_cvt_pk_bf16_f32 v34, v66, v67
	v_cvt_pk_bf16_f32 v35, v50, v51
	v_cvt_pk_bf16_f32 v38, v54, v55
	v_cvt_pk_bf16_f32 v39, v58, v59
	ds_write2_b64 v0, v[34:35], v[38:39] offset0:136 offset1:170
	v_cvt_pk_bf16_f32 v34, v48, v49
	v_cvt_pk_bf16_f32 v35, v52, v53
	v_cvt_pk_bf16_f32 v38, v40, v41
	v_cvt_pk_bf16_f32 v39, v36, v37
	v_cvt_pk_bf16_f32 v44, v88, v89
	v_cvt_pk_bf16_f32 v45, v90, v91
	v_cvt_pk_bf16_f32 v56, v82, v83
	v_cvt_pk_bf16_f32 v57, v86, v87
	ds_write2_b64 v0, v[34:35], v[38:39] offset0:204 offset1:238
	v_or_b32_e32 v38, s13, v120
	v_mov_b64_e32 v[34:35], s[44:45]
	ds_write2_b64 v0, v[44:45], v[56:57] offset1:34
	s_waitcnt lgkmcnt(0)
	s_barrier
	global_load_dword v42, v1, s[16:17]
	v_mad_i64_i32 v[36:37], s[16:17], v38, s73, v[34:35]
	s_lshl_b32 s16, s2, 7
	s_mov_b32 s17, s59
	v_lshl_add_u64 v[36:37], v[36:37], 0, s[16:17]
	v_lshlrev_b32_e32 v0, 1, v106
	v_lshl_add_u64 v[36:37], v[36:37], 0, v[0:1]
	global_load_dwordx2 v[58:59], v[36:37], off offset:800
	global_load_dwordx2 v[56:57], v[36:37], off offset:832
	global_load_dwordx2 v[54:55], v[36:37], off offset:864
	global_load_dwordx2 v[52:53], v[36:37], off offset:896
	v_or_b32_e32 v36, 16, v38
	v_mad_i64_i32 v[34:35], s[18:19], v36, s73, v[34:35]
	v_lshl_add_u64 v[34:35], v[34:35], 0, s[16:17]
	v_lshl_add_u64 v[34:35], v[34:35], 0, v[0:1]
	global_load_dwordx2 v[50:51], v[34:35], off offset:800
	global_load_dwordx2 v[48:49], v[34:35], off offset:832
	global_load_dwordx2 v[46:47], v[34:35], off offset:864
	global_load_dwordx2 v[44:45], v[34:35], off offset:896
	v_pk_mul_f32 v[40:41], v[32:33], v[112:113] op_sel_hi:[1,0]
	v_pk_mul_f32 v[38:39], v[30:31], v[112:113] op_sel_hi:[1,0]
	v_pk_mul_f32 v[36:37], v[28:29], v[112:113] op_sel_hi:[1,0]
	v_pk_mul_f32 v[34:35], v[26:27], v[112:113] op_sel_hi:[1,0]
	v_pk_mul_f32 v[32:33], v[20:21], v[112:113] op_sel_hi:[1,0]
	v_pk_mul_f32 v[30:31], v[18:19], v[112:113] op_sel_hi:[1,0]
	v_pk_mul_f32 v[28:29], v[12:13], v[112:113] op_sel_hi:[1,0]
	v_pk_mul_f32 v[26:27], v[10:11], v[112:113] op_sel_hi:[1,0]
	v_pk_mul_f32 v[20:21], v[24:25], v[110:111] op_sel_hi:[1,0]
	v_pk_mul_f32 v[18:19], v[22:23], v[110:111] op_sel_hi:[1,0]
	v_pk_mul_f32 v[12:13], v[16:17], v[110:111] op_sel_hi:[1,0]
	v_pk_mul_f32 v[10:11], v[14:15], v[110:111] op_sel_hi:[1,0]
	v_add_u32_e32 v0, s72, v124
